# layer-0 x->bf16 streaming copy 4x unrolled (8 x 16B loads in flight per thread) when grid is 256
# baseline (speedup 1.0000x reference)
; DI int otid() { int t = (int)__builtin_amdgcn_workitem_id_x(); asm volatile("" : "+v"(t)); return t; }
; DI u32x4 cvt8(f32x4 a, f32x4 b) { u32x4 o; o[0] = pack2(a[0], a[1]); o[1] = pack2(a[2], a[3]); o[2] = pack2(b[0], b[1]); o[3] = pack2(b[2], b[3]); return o; }
; DI void phase_x2bf(const Ctx& c) {
;   bf16* XB = (bf16*)(c.ws + OFF_XB);
;   for (size_t i = ((size_t)blockIdx.x * NTHR + otid()) * 8; i < (size_t)T * DM; i += (size_t)gridDim.x * NTHR * 8) {
;     const f32x4 a = *(const f32x4*)(c.xin + i), b = *(const f32x4*)(c.xin + i + 4);
;     *(u32x4*)(XB + i) = cvt8(a, b);
;   }
; }
.LBB0_218:
	s_xor_b64 s[4:5], s[0:1], -1
	v_writelane_b32 v226, s4, 17
	s_and_b64 vcc, exec, s[4:5]
	s_nop 0
	v_writelane_b32 v226, s5, 18
	s_cbranch_vccnz .LBB0_229
	v_mov_b32_e32 v6, v186
	v_readlane_b32 s4, v229, 60
	v_readlane_b32 s5, v229, 61
	v_ashrrev_i32_e32 v7, 31, v6
	s_nop 0
	v_lshl_add_u64 v[2:3], v[6:7], 3, s[4:5]
	s_mov_b64 s[4:5], 0x2000000
	v_cmp_gt_u64_e32 vcc, s[4:5], v[2:3]
	s_and_saveexec_b64 s[4:5], vcc
	v_readlane_b32 s10, v228, 60
	v_readlane_b32 s14, v227, 0
	v_readlane_b32 s11, v228, 61
	v_readlane_b32 s15, v227, 1
	s_cbranch_execz .LBB0_222
	v_readlane_b32 s6, v226, 11
	v_lshlrev_b64 v[4:5], 5, v[6:7]
	v_readlane_b32 s7, v226, 12
	s_nop 1
	v_lshl_add_u64 v[4:5], s[6:7], 0, v[4:5]
	v_readlane_b32 s6, v228, 62
	v_readlane_b32 s7, v228, 63
	s_nop 1
	v_lshl_add_u64 v[6:7], v[6:7], 4, s[6:7]
	s_mov_b64 s[6:7], 0
	s_cmp_eq_u32 s76, 0x100
	s_cbranch_scc0 .LBB0_221
	s_movk_i32 s6, 8
.Lx2bf_u:
	global_load_dwordx4 v[8:11], v[4:5], off offset:-16
	global_load_dwordx4 v[12:15], v[4:5], off
	v_lshl_add_u64 v[4:5], v[4:5], 0, s[10:11]
	v_lshl_add_u64 v[2:3], v[2:3], 0, s[22:23]
	global_load_dwordx4 v[230:233], v[4:5], off offset:-16
	global_load_dwordx4 v[234:237], v[4:5], off
	v_lshl_add_u64 v[4:5], v[4:5], 0, s[10:11]
	v_lshl_add_u64 v[2:3], v[2:3], 0, s[22:23]
	global_load_dwordx4 v[238:241], v[4:5], off offset:-16
	global_load_dwordx4 v[242:245], v[4:5], off
	v_lshl_add_u64 v[4:5], v[4:5], 0, s[10:11]
	v_lshl_add_u64 v[2:3], v[2:3], 0, s[22:23]
	global_load_dwordx4 v[246:249], v[4:5], off offset:-16
	global_load_dwordx4 v[250:253], v[4:5], off
	v_lshl_add_u64 v[4:5], v[4:5], 0, s[10:11]
	v_lshl_add_u64 v[2:3], v[2:3], 0, s[22:23]
	s_waitcnt vmcnt(6)
	v_cvt_pk_bf16_f32 v8, v8, v9
	v_cvt_pk_bf16_f32 v9, v10, v11
	v_cvt_pk_bf16_f32 v10, v12, v13
	v_cvt_pk_bf16_f32 v11, v14, v15
	s_waitcnt vmcnt(4)
	v_cvt_pk_bf16_f32 v230, v230, v231
	v_cvt_pk_bf16_f32 v231, v232, v233
	v_cvt_pk_bf16_f32 v232, v234, v235
	v_cvt_pk_bf16_f32 v233, v236, v237
	s_waitcnt vmcnt(2)
	v_cvt_pk_bf16_f32 v238, v238, v239
	v_cvt_pk_bf16_f32 v239, v240, v241
	v_cvt_pk_bf16_f32 v240, v242, v243
	v_cvt_pk_bf16_f32 v241, v244, v245
	s_waitcnt vmcnt(0)
	v_cvt_pk_bf16_f32 v246, v246, v247
	v_cvt_pk_bf16_f32 v247, v248, v249
	v_cvt_pk_bf16_f32 v248, v250, v251
	v_cvt_pk_bf16_f32 v249, v252, v253
	global_store_dwordx4 v[6:7], v[8:11], off
	v_lshl_add_u64 v[6:7], v[6:7], 0, s[14:15]
	global_store_dwordx4 v[6:7], v[230:233], off
	v_lshl_add_u64 v[6:7], v[6:7], 0, s[14:15]
	global_store_dwordx4 v[6:7], v[238:241], off
	v_lshl_add_u64 v[6:7], v[6:7], 0, s[14:15]
	global_store_dwordx4 v[6:7], v[246:249], off
	v_lshl_add_u64 v[6:7], v[6:7], 0, s[14:15]
	s_add_i32 s6, s6, -1
	s_cmp_lg_u32 s6, 0
	s_cbranch_scc1 .Lx2bf_u
	s_branch .LBB0_222
